# G1 peeled first K-tile (C=0, no vmcnt waits) after each epilogue; sparse attn loop LDS prefetch; counted vmcnt at sparse tile top; G1 start skew
# speedup vs baseline: 1.0203x; 1.0035x over previous
.LBB0_212:
	s_ashr_i32 s65, s64, 31
	s_lshl_b64 s[68:69], s[64:65], 19
	s_cmp_eq_u32 s29, 0
	s_cselect_b32 s18, s48, 0
	s_cselect_b32 s15, s49, 0
	s_cselect_b32 s45, s61, 0
	s_cselect_b32 s65, s63, 0
	s_add_u32 s68, s18, s68
	s_addc_u32 s69, s15, s69
	s_and_b64 s[70:71], s[74:75], exec
	s_cselect_b32 s15, s69, s5
	s_cselect_b32 s18, s68, s4
	s_ashr_i32 s67, s66, 31
	s_lshl_b64 s[70:71], s[66:67], 19
	s_add_u32 s70, s45, s70
	s_addc_u32 s71, s65, s71
	s_and_b64 s[74:75], s[74:75], exec
	s_cselect_b32 s45, s71, s73
	s_cselect_b32 s65, s70, s72
	s_add_u32 s4, s4, 0x40080
	s_addc_u32 s5, s5, 0
	s_add_u32 s67, s72, 0x100
	s_addc_u32 s76, s73, 0
	s_mov_b32 s77, -2
	s_cmp_lg_u32 s80, 0
	s_cbranch_scc1 .Lg1_peel
	v_mov_b32_e32 v0, 0
	v_mov_b32_e32 v1, v0
	v_mov_b32_e32 v2, v0
	v_mov_b32_e32 v3, v0
	v_mov_b32_e32 v4, v0
	v_mov_b32_e32 v5, v0
	v_mov_b32_e32 v6, v0
	v_mov_b32_e32 v7, v0
	v_mov_b32_e32 v16, v0
	v_mov_b32_e32 v17, v0
	v_mov_b32_e32 v18, v0
	v_mov_b32_e32 v19, v0
	v_mov_b32_e32 v20, v0
	v_mov_b32_e32 v21, v0
	v_mov_b32_e32 v22, v0
	v_mov_b32_e32 v23, v0
	v_mov_b32_e32 v32, v0
	v_mov_b32_e32 v33, v0
	v_mov_b32_e32 v34, v0
	v_mov_b32_e32 v35, v0
	v_mov_b32_e32 v36, v0
	v_mov_b32_e32 v37, v0
	v_mov_b32_e32 v38, v0
	v_mov_b32_e32 v39, v0
	v_mov_b32_e32 v48, v0
	v_mov_b32_e32 v49, v0
	v_mov_b32_e32 v50, v0
	v_mov_b32_e32 v51, v0
	v_mov_b32_e32 v52, v0
	v_mov_b32_e32 v53, v0
	v_mov_b32_e32 v54, v0
	v_mov_b32_e32 v55, v0
	v_mov_b32_e32 v8, v0
	v_mov_b32_e32 v9, v0
	v_mov_b32_e32 v10, v0
	v_mov_b32_e32 v11, v0
	v_mov_b32_e32 v12, v0
	v_mov_b32_e32 v13, v0
	v_mov_b32_e32 v14, v0
	v_mov_b32_e32 v15, v0
	v_mov_b32_e32 v24, v0
	v_mov_b32_e32 v25, v0
	v_mov_b32_e32 v26, v0
	v_mov_b32_e32 v27, v0
	v_mov_b32_e32 v28, v0
	v_mov_b32_e32 v29, v0
	v_mov_b32_e32 v30, v0
	v_mov_b32_e32 v31, v0
	v_mov_b32_e32 v40, v0
	v_mov_b32_e32 v41, v0
	v_mov_b32_e32 v42, v0
	v_mov_b32_e32 v43, v0
	v_mov_b32_e32 v44, v0
	v_mov_b32_e32 v45, v0
	v_mov_b32_e32 v46, v0
	v_mov_b32_e32 v47, v0
	v_mov_b32_e32 v56, v0
	v_mov_b32_e32 v57, v0
	v_mov_b32_e32 v58, v0
	v_mov_b32_e32 v59, v0
	v_mov_b32_e32 v60, v0
	v_mov_b32_e32 v61, v0
	v_mov_b32_e32 v62, v0
	v_mov_b32_e32 v63, v0
	v_mov_b32_e32 v64, v0
	v_mov_b32_e32 v65, v0
	v_mov_b32_e32 v66, v0
	v_mov_b32_e32 v67, v0
	v_mov_b32_e32 v68, v0
	v_mov_b32_e32 v69, v0
	v_mov_b32_e32 v70, v0
	v_mov_b32_e32 v71, v0
	v_mov_b32_e32 v80, v0
	v_mov_b32_e32 v81, v0
	v_mov_b32_e32 v82, v0
	v_mov_b32_e32 v83, v0
	v_mov_b32_e32 v84, v0
	v_mov_b32_e32 v85, v0
	v_mov_b32_e32 v86, v0
	v_mov_b32_e32 v87, v0
	v_mov_b32_e32 v96, v0
	v_mov_b32_e32 v97, v0
	v_mov_b32_e32 v98, v0
	v_mov_b32_e32 v99, v0
	v_mov_b32_e32 v100, v0
	v_mov_b32_e32 v101, v0
	v_mov_b32_e32 v102, v0
	v_mov_b32_e32 v103, v0
	v_mov_b32_e32 v112, v0
	v_mov_b32_e32 v113, v0
	v_mov_b32_e32 v114, v0
	v_mov_b32_e32 v115, v0
	v_mov_b32_e32 v116, v0
	v_mov_b32_e32 v117, v0
	v_mov_b32_e32 v118, v0
	v_mov_b32_e32 v119, v0
	v_mov_b32_e32 v72, v0
	v_mov_b32_e32 v73, v0
	v_mov_b32_e32 v74, v0
	v_mov_b32_e32 v75, v0
	v_mov_b32_e32 v76, v0
	v_mov_b32_e32 v77, v0
	v_mov_b32_e32 v78, v0
	v_mov_b32_e32 v79, v0
	v_mov_b32_e32 v88, v0
	v_mov_b32_e32 v89, v0
	v_mov_b32_e32 v90, v0
	v_mov_b32_e32 v91, v0
	v_mov_b32_e32 v92, v0
	v_mov_b32_e32 v93, v0
	v_mov_b32_e32 v94, v0
	v_mov_b32_e32 v95, v0
	v_mov_b32_e32 v104, v0
	v_mov_b32_e32 v105, v0
	v_mov_b32_e32 v106, v0
	v_mov_b32_e32 v107, v0
	v_mov_b32_e32 v108, v0
	v_mov_b32_e32 v109, v0
	v_mov_b32_e32 v110, v0
	v_mov_b32_e32 v111, v0
	v_mov_b32_e32 v120, v0
	v_mov_b32_e32 v121, v0
	v_mov_b32_e32 v122, v0
	v_mov_b32_e32 v123, v0
	v_mov_b32_e32 v124, v0
	v_mov_b32_e32 v125, v0
	v_mov_b32_e32 v126, v0
	v_mov_b32_e32 v127, v0
	s_branch .LBB0_213
.Lg1_peel:
	ds_read_b128 v[128:131], v175
	ds_read_b128 v[132:135], v175 offset:1024
	ds_read_b128 v[150:153], v175 offset:2048
	ds_read_b128 v[154:157], v175 offset:3072
	ds_read_b128 v[186:189], v177
	ds_read_b128 v[190:193], v177 offset:1024
	ds_read_b128 v[194:197], v177 offset:2048
	ds_read_b128 v[198:201], v177 offset:3072
	s_add_u32 s72, s4, 0xfffc0080
	s_addc_u32 s73, s5, -1
	s_cmp_eq_u32 s77, 12
	s_cselect_b32 s75, s15, s73
	s_cselect_b32 s74, s18, s72
	s_cselect_b32 s73, s45, s76
	s_cselect_b32 s72, s65, s67
	v_lshl_add_u64 v[158:159], s[4:5], 0, v[146:147]
	s_add_i32 m0, s17, 0xc000
	ds_read_b128 v[202:205], v179
	ds_read_b128 v[206:209], v179 offset:1024
	ds_read_b128 v[210:213], v179 offset:2048
	ds_read_b128 v[214:217], v179 offset:3072
	ds_read_b128 v[218:221], v179 offset:4096
	ds_read_b128 v[222:225], v179 offset:5120
	ds_read_b128 v[230:233], v179 offset:6144
	ds_read_b128 v[234:237], v179 offset:7168
	global_load_lds_dwordx4 v[158:159], off
	v_lshl_add_u64 v[158:159], s[4:5], 0, v[148:149]
	s_add_i32 m0, s17, 0xe000
	s_nop 0
	global_load_lds_dwordx4 v[158:159], off
	s_waitcnt lgkmcnt(0)
	s_barrier
	s_setprio 1
	s_waitcnt lgkmcnt(0)
	v_mfma_f32_16x16x32_bf16 v[124:127], v[128:131], v[202:205], 0
	v_mfma_f32_16x16x32_bf16 v[120:123], v[150:153], v[202:205], 0
	v_mfma_f32_16x16x32_bf16 v[108:111], v[128:131], v[210:213], 0
	v_mfma_f32_16x16x32_bf16 v[104:107], v[150:153], v[210:213], 0
	v_mfma_f32_16x16x32_bf16 v[92:95], v[128:131], v[218:221], 0
	v_mfma_f32_16x16x32_bf16 v[88:91], v[150:153], v[218:221], 0
	v_mfma_f32_16x16x32_bf16 v[76:79], v[128:131], v[230:233], 0
	v_mfma_f32_16x16x32_bf16 v[72:75], v[150:153], v[230:233], 0
	v_mfma_f32_16x16x32_bf16 v[124:127], v[132:135], v[206:209], v[124:127]
	v_mfma_f32_16x16x32_bf16 v[120:123], v[154:157], v[206:209], v[120:123]
	v_mfma_f32_16x16x32_bf16 v[108:111], v[132:135], v[214:217], v[108:111]
	v_mfma_f32_16x16x32_bf16 v[104:107], v[154:157], v[214:217], v[104:107]
	v_mfma_f32_16x16x32_bf16 v[92:95], v[132:135], v[222:225], v[92:95]
	v_mfma_f32_16x16x32_bf16 v[88:91], v[154:157], v[222:225], v[88:91]
	v_mfma_f32_16x16x32_bf16 v[76:79], v[132:135], v[234:237], v[76:79]
	v_mfma_f32_16x16x32_bf16 v[72:75], v[154:157], v[234:237], v[72:75]
	s_setprio 0
	s_setprio 1
	v_mfma_f32_16x16x32_bf16 v[116:119], v[186:189], v[202:205], 0
	v_mfma_f32_16x16x32_bf16 v[112:115], v[194:197], v[202:205], 0
	v_mfma_f32_16x16x32_bf16 v[100:103], v[186:189], v[210:213], 0
	v_mfma_f32_16x16x32_bf16 v[96:99], v[194:197], v[210:213], 0
	v_mfma_f32_16x16x32_bf16 v[84:87], v[186:189], v[218:221], 0
	v_mfma_f32_16x16x32_bf16 v[80:83], v[194:197], v[218:221], 0
	v_mfma_f32_16x16x32_bf16 v[68:71], v[186:189], v[230:233], 0
	v_mfma_f32_16x16x32_bf16 v[64:67], v[194:197], v[230:233], 0
	v_mfma_f32_16x16x32_bf16 v[116:119], v[190:193], v[206:209], v[116:119]
	v_mfma_f32_16x16x32_bf16 v[112:115], v[198:201], v[206:209], v[112:115]
	v_mfma_f32_16x16x32_bf16 v[100:103], v[190:193], v[214:217], v[100:103]
	v_mfma_f32_16x16x32_bf16 v[96:99], v[198:201], v[214:217], v[96:99]
	v_mfma_f32_16x16x32_bf16 v[84:87], v[190:193], v[222:225], v[84:87]
	v_mfma_f32_16x16x32_bf16 v[80:83], v[198:201], v[222:225], v[80:83]
	v_mfma_f32_16x16x32_bf16 v[68:71], v[190:193], v[234:237], v[68:71]
	v_mfma_f32_16x16x32_bf16 v[64:67], v[198:201], v[234:237], v[64:67]
	s_setprio 0
	s_barrier
	s_add_i32 vcc_lo, s30, s53
	v_lshl_add_u64 v[158:159], s[72:73], 0, v[138:139]
	s_mov_b32 m0, vcc_lo
	ds_read_b128 v[202:205], v179 offset:16384
	ds_read_b128 v[206:209], v179 offset:17408
	ds_read_b128 v[210:213], v179 offset:18432
	ds_read_b128 v[214:217], v179 offset:19456
	ds_read_b128 v[218:221], v179 offset:20480
	ds_read_b128 v[222:225], v179 offset:21504
	ds_read_b128 v[230:233], v179 offset:22528
	ds_read_b128 v[234:237], v179 offset:23552
	global_load_lds_dwordx4 v[158:159], off
	s_add_i32 m0, vcc_lo, 0x2000
	s_add_u32 vcc_lo, s72, 0x40000
	v_lshl_add_u64 v[180:181], s[72:73], 0, v[142:143]
	s_addc_u32 vcc_hi, s73, 0
	s_add_i32 s79, s31, s53
	global_load_lds_dwordx4 v[180:181], off
	v_lshl_add_u64 v[226:227], vcc, 0, v[138:139]
	s_mov_b32 m0, s79
	v_lshl_add_u64 v[238:239], s[74:75], 0, v[140:141]
	global_load_lds_dwordx4 v[226:227], off
	v_lshl_add_u64 v[226:227], vcc, 0, v[142:143]
	s_add_i32 m0, s79, 0x2000
	s_nop 0
	global_load_lds_dwordx4 v[226:227], off
	v_lshl_add_u64 v[226:227], s[74:75], 0, v[136:137]
	s_mov_b32 m0, s17
	s_nop 0
	global_load_lds_dwordx4 v[226:227], off
	s_mov_b32 m0, s81
	s_nop 0
	global_load_lds_dwordx4 v[238:239], off
	s_waitcnt lgkmcnt(0)
	s_barrier
	s_setprio 1
	s_waitcnt lgkmcnt(0)
	v_mfma_f32_16x16x32_bf16 v[60:63], v[128:131], v[202:205], 0
	v_mfma_f32_16x16x32_bf16 v[56:59], v[150:153], v[202:205], 0
	v_mfma_f32_16x16x32_bf16 v[44:47], v[128:131], v[210:213], 0
	v_mfma_f32_16x16x32_bf16 v[40:43], v[150:153], v[210:213], 0
	v_mfma_f32_16x16x32_bf16 v[28:31], v[128:131], v[218:221], 0
	v_mfma_f32_16x16x32_bf16 v[24:27], v[150:153], v[218:221], 0
	v_mfma_f32_16x16x32_bf16 v[12:15], v[128:131], v[230:233], 0
	v_mfma_f32_16x16x32_bf16 v[8:11], v[150:153], v[230:233], 0
	v_mfma_f32_16x16x32_bf16 v[60:63], v[132:135], v[206:209], v[60:63]
	v_mfma_f32_16x16x32_bf16 v[56:59], v[154:157], v[206:209], v[56:59]
	v_mfma_f32_16x16x32_bf16 v[44:47], v[132:135], v[214:217], v[44:47]
	v_mfma_f32_16x16x32_bf16 v[40:43], v[154:157], v[214:217], v[40:43]
	v_mfma_f32_16x16x32_bf16 v[28:31], v[132:135], v[222:225], v[28:31]
	v_mfma_f32_16x16x32_bf16 v[24:27], v[154:157], v[222:225], v[24:27]
	v_mfma_f32_16x16x32_bf16 v[12:15], v[132:135], v[234:237], v[12:15]
	v_mfma_f32_16x16x32_bf16 v[8:11], v[154:157], v[234:237], v[8:11]
	s_setprio 0
	s_setprio 1
	v_mfma_f32_16x16x32_bf16 v[52:55], v[186:189], v[202:205], 0
	v_mfma_f32_16x16x32_bf16 v[48:51], v[194:197], v[202:205], 0
	v_mfma_f32_16x16x32_bf16 v[36:39], v[186:189], v[210:213], 0
	v_mfma_f32_16x16x32_bf16 v[32:35], v[194:197], v[210:213], 0
	v_mfma_f32_16x16x32_bf16 v[20:23], v[186:189], v[218:221], 0
	v_mfma_f32_16x16x32_bf16 v[16:19], v[194:197], v[218:221], 0
	v_mfma_f32_16x16x32_bf16 v[4:7], v[186:189], v[230:233], 0
	v_mfma_f32_16x16x32_bf16 v[0:3], v[194:197], v[230:233], 0
	v_mfma_f32_16x16x32_bf16 v[52:55], v[190:193], v[206:209], v[52:55]
	v_mfma_f32_16x16x32_bf16 v[48:51], v[198:201], v[206:209], v[48:51]
	v_mfma_f32_16x16x32_bf16 v[36:39], v[190:193], v[214:217], v[36:39]
	v_mfma_f32_16x16x32_bf16 v[32:35], v[198:201], v[214:217], v[32:35]
	v_mfma_f32_16x16x32_bf16 v[20:23], v[190:193], v[222:225], v[20:23]
	v_mfma_f32_16x16x32_bf16 v[16:19], v[198:201], v[222:225], v[16:19]
	v_mfma_f32_16x16x32_bf16 v[4:7], v[190:193], v[234:237], v[4:7]
	v_mfma_f32_16x16x32_bf16 v[0:3], v[198:201], v[234:237], v[0:3]
	s_setprio 0
	s_barrier
	s_branch .Lg1_mid
.LBB0_213:
	ds_read_b128 v[128:131], v175
	ds_read_b128 v[132:135], v175 offset:1024
	ds_read_b128 v[150:153], v175 offset:2048
	ds_read_b128 v[154:157], v175 offset:3072
	ds_read_b128 v[186:189], v177
	ds_read_b128 v[190:193], v177 offset:1024
	ds_read_b128 v[194:197], v177 offset:2048
	ds_read_b128 v[198:201], v177 offset:3072
	s_add_u32 s72, s4, 0xfffc0080
	s_addc_u32 s73, s5, -1
	s_cmp_eq_u32 s77, 12
	s_cselect_b32 s75, s15, s73
	s_cselect_b32 s74, s18, s72
	s_cselect_b32 s73, s45, s76
	s_cselect_b32 s72, s65, s67
	v_lshl_add_u64 v[158:159], s[4:5], 0, v[146:147]
	s_add_i32 m0, s17, 0xc000
	ds_read_b128 v[202:205], v179
	ds_read_b128 v[206:209], v179 offset:1024
	ds_read_b128 v[210:213], v179 offset:2048
	ds_read_b128 v[214:217], v179 offset:3072
	ds_read_b128 v[218:221], v179 offset:4096
	ds_read_b128 v[222:225], v179 offset:5120
	ds_read_b128 v[230:233], v179 offset:6144
	ds_read_b128 v[234:237], v179 offset:7168
	global_load_lds_dwordx4 v[158:159], off
	v_lshl_add_u64 v[158:159], s[4:5], 0, v[148:149]
	s_add_i32 m0, s17, 0xe000
	s_nop 0
	global_load_lds_dwordx4 v[158:159], off
	s_waitcnt vmcnt(8)
	s_waitcnt lgkmcnt(0)
	s_barrier
	s_setprio 1
	s_waitcnt lgkmcnt(0)
	v_mfma_f32_16x16x32_bf16 v[124:127], v[128:131], v[202:205], v[124:127]
	v_mfma_f32_16x16x32_bf16 v[120:123], v[150:153], v[202:205], v[120:123]
	v_mfma_f32_16x16x32_bf16 v[108:111], v[128:131], v[210:213], v[108:111]
	v_mfma_f32_16x16x32_bf16 v[104:107], v[150:153], v[210:213], v[104:107]
	v_mfma_f32_16x16x32_bf16 v[92:95], v[128:131], v[218:221], v[92:95]
	v_mfma_f32_16x16x32_bf16 v[88:91], v[150:153], v[218:221], v[88:91]
	v_mfma_f32_16x16x32_bf16 v[76:79], v[128:131], v[230:233], v[76:79]
	v_mfma_f32_16x16x32_bf16 v[72:75], v[150:153], v[230:233], v[72:75]
	v_mfma_f32_16x16x32_bf16 v[124:127], v[132:135], v[206:209], v[124:127]
	v_mfma_f32_16x16x32_bf16 v[120:123], v[154:157], v[206:209], v[120:123]
	v_mfma_f32_16x16x32_bf16 v[108:111], v[132:135], v[214:217], v[108:111]
	v_mfma_f32_16x16x32_bf16 v[104:107], v[154:157], v[214:217], v[104:107]
	v_mfma_f32_16x16x32_bf16 v[92:95], v[132:135], v[222:225], v[92:95]
	v_mfma_f32_16x16x32_bf16 v[88:91], v[154:157], v[222:225], v[88:91]
	v_mfma_f32_16x16x32_bf16 v[76:79], v[132:135], v[234:237], v[76:79]
	v_mfma_f32_16x16x32_bf16 v[72:75], v[154:157], v[234:237], v[72:75]
	s_setprio 0
	s_setprio 1
	v_mfma_f32_16x16x32_bf16 v[116:119], v[186:189], v[202:205], v[116:119]
	v_mfma_f32_16x16x32_bf16 v[112:115], v[194:197], v[202:205], v[112:115]
	v_mfma_f32_16x16x32_bf16 v[100:103], v[186:189], v[210:213], v[100:103]
	v_mfma_f32_16x16x32_bf16 v[96:99], v[194:197], v[210:213], v[96:99]
	v_mfma_f32_16x16x32_bf16 v[84:87], v[186:189], v[218:221], v[84:87]
	v_mfma_f32_16x16x32_bf16 v[80:83], v[194:197], v[218:221], v[80:83]
	v_mfma_f32_16x16x32_bf16 v[68:71], v[186:189], v[230:233], v[68:71]
	v_mfma_f32_16x16x32_bf16 v[64:67], v[194:197], v[230:233], v[64:67]
	v_mfma_f32_16x16x32_bf16 v[116:119], v[190:193], v[206:209], v[116:119]
	v_mfma_f32_16x16x32_bf16 v[112:115], v[198:201], v[206:209], v[112:115]
	v_mfma_f32_16x16x32_bf16 v[100:103], v[190:193], v[214:217], v[100:103]
	v_mfma_f32_16x16x32_bf16 v[96:99], v[198:201], v[214:217], v[96:99]
	v_mfma_f32_16x16x32_bf16 v[84:87], v[190:193], v[222:225], v[84:87]
	v_mfma_f32_16x16x32_bf16 v[80:83], v[198:201], v[222:225], v[80:83]
	v_mfma_f32_16x16x32_bf16 v[68:71], v[190:193], v[234:237], v[68:71]
	v_mfma_f32_16x16x32_bf16 v[64:67], v[198:201], v[234:237], v[64:67]
	s_setprio 0
	s_barrier
	s_add_i32 vcc_lo, s30, s53
	v_lshl_add_u64 v[158:159], s[72:73], 0, v[138:139]
	s_mov_b32 m0, vcc_lo
	ds_read_b128 v[202:205], v179 offset:16384
	ds_read_b128 v[206:209], v179 offset:17408
	ds_read_b128 v[210:213], v179 offset:18432
	ds_read_b128 v[214:217], v179 offset:19456
	ds_read_b128 v[218:221], v179 offset:20480
	ds_read_b128 v[222:225], v179 offset:21504
	ds_read_b128 v[230:233], v179 offset:22528
	ds_read_b128 v[234:237], v179 offset:23552
	global_load_lds_dwordx4 v[158:159], off
	s_add_i32 m0, vcc_lo, 0x2000
	s_add_u32 vcc_lo, s72, 0x40000
	v_lshl_add_u64 v[180:181], s[72:73], 0, v[142:143]
	s_addc_u32 vcc_hi, s73, 0
	s_add_i32 s79, s31, s53
	global_load_lds_dwordx4 v[180:181], off
	v_lshl_add_u64 v[226:227], vcc, 0, v[138:139]
	s_mov_b32 m0, s79
	v_lshl_add_u64 v[238:239], s[74:75], 0, v[140:141]
	global_load_lds_dwordx4 v[226:227], off
	v_lshl_add_u64 v[226:227], vcc, 0, v[142:143]
	s_add_i32 m0, s79, 0x2000
	s_nop 0
	global_load_lds_dwordx4 v[226:227], off
	v_lshl_add_u64 v[226:227], s[74:75], 0, v[136:137]
	s_mov_b32 m0, s17
	s_nop 0
	global_load_lds_dwordx4 v[226:227], off
	s_mov_b32 m0, s81
	s_nop 0
	global_load_lds_dwordx4 v[238:239], off
	s_waitcnt vmcnt(8)
	s_waitcnt lgkmcnt(0)
	s_barrier
	s_setprio 1
	s_waitcnt lgkmcnt(0)
	v_mfma_f32_16x16x32_bf16 v[60:63], v[128:131], v[202:205], v[60:63]
	v_mfma_f32_16x16x32_bf16 v[56:59], v[150:153], v[202:205], v[56:59]
	v_mfma_f32_16x16x32_bf16 v[44:47], v[128:131], v[210:213], v[44:47]
	v_mfma_f32_16x16x32_bf16 v[40:43], v[150:153], v[210:213], v[40:43]
	v_mfma_f32_16x16x32_bf16 v[28:31], v[128:131], v[218:221], v[28:31]
	v_mfma_f32_16x16x32_bf16 v[24:27], v[150:153], v[218:221], v[24:27]
	v_mfma_f32_16x16x32_bf16 v[12:15], v[128:131], v[230:233], v[12:15]
	v_mfma_f32_16x16x32_bf16 v[8:11], v[150:153], v[230:233], v[8:11]
	v_mfma_f32_16x16x32_bf16 v[60:63], v[132:135], v[206:209], v[60:63]
	v_mfma_f32_16x16x32_bf16 v[56:59], v[154:157], v[206:209], v[56:59]
	v_mfma_f32_16x16x32_bf16 v[44:47], v[132:135], v[214:217], v[44:47]
	v_mfma_f32_16x16x32_bf16 v[40:43], v[154:157], v[214:217], v[40:43]
	v_mfma_f32_16x16x32_bf16 v[28:31], v[132:135], v[222:225], v[28:31]
	v_mfma_f32_16x16x32_bf16 v[24:27], v[154:157], v[222:225], v[24:27]
	v_mfma_f32_16x16x32_bf16 v[12:15], v[132:135], v[234:237], v[12:15]
	v_mfma_f32_16x16x32_bf16 v[8:11], v[154:157], v[234:237], v[8:11]
	s_setprio 0
	s_setprio 1
	v_mfma_f32_16x16x32_bf16 v[52:55], v[186:189], v[202:205], v[52:55]
	v_mfma_f32_16x16x32_bf16 v[48:51], v[194:197], v[202:205], v[48:51]
	v_mfma_f32_16x16x32_bf16 v[36:39], v[186:189], v[210:213], v[36:39]
	v_mfma_f32_16x16x32_bf16 v[32:35], v[194:197], v[210:213], v[32:35]
	v_mfma_f32_16x16x32_bf16 v[20:23], v[186:189], v[218:221], v[20:23]
	v_mfma_f32_16x16x32_bf16 v[16:19], v[194:197], v[218:221], v[16:19]
	v_mfma_f32_16x16x32_bf16 v[4:7], v[186:189], v[230:233], v[4:7]
	v_mfma_f32_16x16x32_bf16 v[0:3], v[194:197], v[230:233], v[0:3]
	v_mfma_f32_16x16x32_bf16 v[52:55], v[190:193], v[206:209], v[52:55]
	v_mfma_f32_16x16x32_bf16 v[48:51], v[198:201], v[206:209], v[48:51]
	v_mfma_f32_16x16x32_bf16 v[36:39], v[190:193], v[214:217], v[36:39]
	v_mfma_f32_16x16x32_bf16 v[32:35], v[198:201], v[214:217], v[32:35]
	v_mfma_f32_16x16x32_bf16 v[20:23], v[190:193], v[222:225], v[20:23]
	v_mfma_f32_16x16x32_bf16 v[16:19], v[198:201], v[222:225], v[16:19]
	v_mfma_f32_16x16x32_bf16 v[4:7], v[190:193], v[234:237], v[4:7]
	v_mfma_f32_16x16x32_bf16 v[0:3], v[198:201], v[234:237], v[0:3]
	s_setprio 0
	s_barrier
.Lg1_mid:
	s_add_i32 s79, 0, 0x18000
	v_add_u32_e32 v144, s79, v161
	s_add_i32 vcc_lo, 0, 0x1c000
	ds_read_b128 v[128:131], v144
	ds_read_b128 v[132:135], v144 offset:1024
	ds_read_b128 v[150:153], v144 offset:2048
	ds_read_b128 v[154:157], v144 offset:3072
	v_add_u32_e32 v144, vcc_lo, v161
	ds_read_b128 v[186:189], v144
	ds_read_b128 v[190:193], v144 offset:1024
	ds_read_b128 v[194:197], v144 offset:2048
	ds_read_b128 v[198:201], v144 offset:3072
	s_add_u32 s74, s74, 0x40000
	s_addc_u32 s75, s75, 0
	s_mov_b32 m0, s82
	v_lshl_add_u64 v[240:241], s[74:75], 0, v[136:137]
	ds_read_b128 v[202:205], v179 offset:32768
	ds_read_b128 v[206:209], v179 offset:33792
	ds_read_b128 v[210:213], v179 offset:34816
	ds_read_b128 v[214:217], v179 offset:35840
	ds_read_b128 v[218:221], v179 offset:36864
	ds_read_b128 v[222:225], v179 offset:37888
	ds_read_b128 v[230:233], v179 offset:38912
	ds_read_b128 v[234:237], v179 offset:39936
	global_load_lds_dwordx4 v[240:241], off
	v_lshl_add_u64 v[240:241], s[74:75], 0, v[140:141]
	s_mov_b32 m0, s83
	s_nop 0
	global_load_lds_dwordx4 v[240:241], off
	s_waitcnt vmcnt(8)
	s_waitcnt lgkmcnt(0)
	s_barrier
	s_setprio 1
	s_waitcnt lgkmcnt(0)
	v_mfma_f32_16x16x32_bf16 v[124:127], v[128:131], v[202:205], v[124:127]
	v_mfma_f32_16x16x32_bf16 v[120:123], v[150:153], v[202:205], v[120:123]
	v_mfma_f32_16x16x32_bf16 v[108:111], v[128:131], v[210:213], v[108:111]
	v_mfma_f32_16x16x32_bf16 v[104:107], v[150:153], v[210:213], v[104:107]
	v_mfma_f32_16x16x32_bf16 v[92:95], v[128:131], v[218:221], v[92:95]
	v_mfma_f32_16x16x32_bf16 v[88:91], v[150:153], v[218:221], v[88:91]
	v_mfma_f32_16x16x32_bf16 v[76:79], v[128:131], v[230:233], v[76:79]
	v_mfma_f32_16x16x32_bf16 v[72:75], v[150:153], v[230:233], v[72:75]
	v_mfma_f32_16x16x32_bf16 v[124:127], v[132:135], v[206:209], v[124:127]
	v_mfma_f32_16x16x32_bf16 v[120:123], v[154:157], v[206:209], v[120:123]
	v_mfma_f32_16x16x32_bf16 v[108:111], v[132:135], v[214:217], v[108:111]
	v_mfma_f32_16x16x32_bf16 v[104:107], v[154:157], v[214:217], v[104:107]
	v_mfma_f32_16x16x32_bf16 v[92:95], v[132:135], v[222:225], v[92:95]
	v_mfma_f32_16x16x32_bf16 v[88:91], v[154:157], v[222:225], v[88:91]
	v_mfma_f32_16x16x32_bf16 v[76:79], v[132:135], v[234:237], v[76:79]
	v_mfma_f32_16x16x32_bf16 v[72:75], v[154:157], v[234:237], v[72:75]
	s_setprio 0
	s_setprio 1
	v_mfma_f32_16x16x32_bf16 v[116:119], v[186:189], v[202:205], v[116:119]
	v_mfma_f32_16x16x32_bf16 v[112:115], v[194:197], v[202:205], v[112:115]
	v_mfma_f32_16x16x32_bf16 v[100:103], v[186:189], v[210:213], v[100:103]
	v_mfma_f32_16x16x32_bf16 v[96:99], v[194:197], v[210:213], v[96:99]
	v_mfma_f32_16x16x32_bf16 v[84:87], v[186:189], v[218:221], v[84:87]
	v_mfma_f32_16x16x32_bf16 v[80:83], v[194:197], v[218:221], v[80:83]
	v_mfma_f32_16x16x32_bf16 v[68:71], v[186:189], v[230:233], v[68:71]
	v_mfma_f32_16x16x32_bf16 v[64:67], v[194:197], v[230:233], v[64:67]
	v_mfma_f32_16x16x32_bf16 v[116:119], v[190:193], v[206:209], v[116:119]
	v_mfma_f32_16x16x32_bf16 v[112:115], v[198:201], v[206:209], v[112:115]
	v_mfma_f32_16x16x32_bf16 v[100:103], v[190:193], v[214:217], v[100:103]
	v_mfma_f32_16x16x32_bf16 v[96:99], v[198:201], v[214:217], v[96:99]
	v_mfma_f32_16x16x32_bf16 v[84:87], v[190:193], v[222:225], v[84:87]
	v_mfma_f32_16x16x32_bf16 v[80:83], v[198:201], v[222:225], v[80:83]
	v_mfma_f32_16x16x32_bf16 v[68:71], v[190:193], v[234:237], v[68:71]
	v_mfma_f32_16x16x32_bf16 v[64:67], v[198:201], v[234:237], v[64:67]
	s_setprio 0
	s_barrier
	s_add_i32 s74, s79, s53
	v_lshl_add_u64 v[158:159], v[158:159], 0, s[24:25]
	s_mov_b32 m0, s74
	ds_read_b128 v[202:205], v179 offset:49152
	ds_read_b128 v[206:209], v179 offset:50176
	ds_read_b128 v[210:213], v179 offset:51200
	ds_read_b128 v[214:217], v179 offset:52224
	ds_read_b128 v[218:221], v179 offset:53248
	ds_read_b128 v[222:225], v179 offset:54272
	ds_read_b128 v[230:233], v179 offset:55296
	ds_read_b128 v[234:237], v179 offset:56320
	global_load_lds_dwordx4 v[158:159], off
	s_add_i32 m0, s74, 0x2000
	s_add_u32 s72, s72, 0x40080
	v_lshl_add_u64 v[158:159], v[180:181], 0, s[24:25]
	s_addc_u32 s73, s73, 0
	s_add_i32 s74, vcc_lo, s53
	global_load_lds_dwordx4 v[158:159], off
	v_lshl_add_u64 v[158:159], s[72:73], 0, v[138:139]
	s_mov_b32 m0, s74
	s_nop 0
	global_load_lds_dwordx4 v[158:159], off
	v_lshl_add_u64 v[158:159], s[72:73], 0, v[142:143]
	s_add_i32 m0, s74, 0x2000
	s_nop 0
	global_load_lds_dwordx4 v[158:159], off
	v_lshl_add_u64 v[158:159], v[226:227], 0, s[24:25]
	s_mov_b32 m0, s86
	s_nop 0
	global_load_lds_dwordx4 v[158:159], off
	v_lshl_add_u64 v[158:159], v[238:239], 0, s[24:25]
	s_mov_b32 m0, s87
	s_nop 0
	global_load_lds_dwordx4 v[158:159], off
	s_waitcnt vmcnt(8)
	s_waitcnt lgkmcnt(0)
	s_barrier
	s_setprio 1
	s_waitcnt lgkmcnt(0)
	v_mfma_f32_16x16x32_bf16 v[60:63], v[128:131], v[202:205], v[60:63]
	v_mfma_f32_16x16x32_bf16 v[56:59], v[150:153], v[202:205], v[56:59]
	v_mfma_f32_16x16x32_bf16 v[44:47], v[128:131], v[210:213], v[44:47]
	v_mfma_f32_16x16x32_bf16 v[40:43], v[150:153], v[210:213], v[40:43]
	v_mfma_f32_16x16x32_bf16 v[28:31], v[128:131], v[218:221], v[28:31]
	v_mfma_f32_16x16x32_bf16 v[24:27], v[150:153], v[218:221], v[24:27]
	v_mfma_f32_16x16x32_bf16 v[12:15], v[128:131], v[230:233], v[12:15]
	v_mfma_f32_16x16x32_bf16 v[8:11], v[150:153], v[230:233], v[8:11]
	v_mfma_f32_16x16x32_bf16 v[60:63], v[132:135], v[206:209], v[60:63]
	v_mfma_f32_16x16x32_bf16 v[56:59], v[154:157], v[206:209], v[56:59]
	v_mfma_f32_16x16x32_bf16 v[44:47], v[132:135], v[214:217], v[44:47]
	v_mfma_f32_16x16x32_bf16 v[40:43], v[154:157], v[214:217], v[40:43]
	v_mfma_f32_16x16x32_bf16 v[28:31], v[132:135], v[222:225], v[28:31]
	v_mfma_f32_16x16x32_bf16 v[24:27], v[154:157], v[222:225], v[24:27]
	v_mfma_f32_16x16x32_bf16 v[12:15], v[132:135], v[234:237], v[12:15]
	v_mfma_f32_16x16x32_bf16 v[8:11], v[154:157], v[234:237], v[8:11]
	s_setprio 0
	s_setprio 1
	v_mfma_f32_16x16x32_bf16 v[52:55], v[186:189], v[202:205], v[52:55]
	v_mfma_f32_16x16x32_bf16 v[48:51], v[194:197], v[202:205], v[48:51]
	v_mfma_f32_16x16x32_bf16 v[36:39], v[186:189], v[210:213], v[36:39]
	v_mfma_f32_16x16x32_bf16 v[32:35], v[194:197], v[210:213], v[32:35]
	v_mfma_f32_16x16x32_bf16 v[20:23], v[186:189], v[218:221], v[20:23]
	v_mfma_f32_16x16x32_bf16 v[16:19], v[194:197], v[218:221], v[16:19]
	v_mfma_f32_16x16x32_bf16 v[4:7], v[186:189], v[230:233], v[4:7]
	v_mfma_f32_16x16x32_bf16 v[0:3], v[194:197], v[230:233], v[0:3]
	v_mfma_f32_16x16x32_bf16 v[52:55], v[190:193], v[206:209], v[52:55]
	v_mfma_f32_16x16x32_bf16 v[48:51], v[198:201], v[206:209], v[48:51]
	v_mfma_f32_16x16x32_bf16 v[36:39], v[190:193], v[214:217], v[36:39]
	v_mfma_f32_16x16x32_bf16 v[32:35], v[198:201], v[214:217], v[32:35]
	v_mfma_f32_16x16x32_bf16 v[20:23], v[190:193], v[222:225], v[20:23]
	v_mfma_f32_16x16x32_bf16 v[16:19], v[198:201], v[222:225], v[16:19]
	v_mfma_f32_16x16x32_bf16 v[4:7], v[190:193], v[234:237], v[4:7]
	v_mfma_f32_16x16x32_bf16 v[0:3], v[198:201], v[234:237], v[0:3]
	s_setprio 0
	s_barrier
	s_add_i32 s77, s77, 2
	s_add_u32 s4, s4, 0x100
	s_addc_u32 s5, s5, 0
	s_add_u32 s67, s67, 0x100
	s_addc_u32 s76, s76, 0
	s_cmp_gt_u32 s77, 13
	s_cbranch_scc0 .LBB0_213
	s_and_b64 vcc, exec, s[34:35]
	s_cbranch_vccz .LBB0_216
	s_barrier

.LBB0_782:
.LBB0_783:
	s_mov_b32 s98, 0
	s_cmp_gt_i32 s42, 6
	s_cselect_b64 s[14:15], -1, 0
	s_cmp_lt_i32 s42, 7
	s_cselect_b64 s[4:5], -1, 0
	s_cmp_gt_i32 s43, 6
	s_cselect_b64 s[6:7], -1, 0
	s_and_b64 s[4:5], s[4:5], s[6:7]
	s_andn2_b64 vcc, exec, s[4:5]
	s_cbranch_vccnz .LBB0_860
	s_and_b32 s4, s33, 0xffffffc0
	s_waitcnt vmcnt(0)
	v_mbcnt_hi_u32_b32 v6, -1, v252
	v_add_u32_e32 v0, s4, v6
	s_load_dwordx2 s[30:31], s[0:1], 0xb0
	s_andn2_b64 vcc, exec, s[80:81]
	s_cbranch_vccz .LBB0_786
	s_movk_i32 s4, 0x400
	v_cmp_gt_i32_e32 vcc, s4, v0
	s_and_saveexec_b64 s[4:5], vcc
	s_cbranch_execnz .LBB0_787
	s_branch .LBB0_789

.LBB0_824:
	s_lshl_b32 s6, s68, 2
	s_add_i32 s6, s6, 0
	s_add_i32 s7, s6, 0x21400
	s_waitcnt lgkmcnt(0)
	v_mov_b32_e32 v0, s7
	s_add_i32 s6, s6, 0x20400
	v_mov_b32_e32 v1, s6
	ds_read_b32 v3, v0
	ds_read_b32 v2, v1
	s_mov_b32 s12, s65
	s_mov_b32 s65, s68
	s_ashr_i32 s68, s68, 5
	s_cmp_eq_u32 s98, 9
	s_cbranch_scc1 .Lsp_w9
	s_waitcnt vmcnt(0)
	s_branch .Lsp_wd
.Lsp_w9:
	s_waitcnt vmcnt(9)
.Lsp_wd:
	s_mov_b32 s98, 0
	v_mov_b32_e32 v206, v147
	s_mov_b64 s[6:7], 0
	s_cmp_eq_u32 s65, s12
	s_mov_b64 s[30:31], -1
	s_cbranch_scc1 .LBB0_826
	s_ashr_i32 s6, s65, 8
	s_ashr_i32 s7, s6, 31
	s_lshl_b32 s12, s65, 8
	s_lshl_b64 s[6:7], s[6:7], 13
	s_and_b32 s12, s12, 0x1f00
	s_or_b32 s6, s6, s12
	s_lshl_b32 s12, s68, 8
	s_and_b32 s12, s12, 0x700
	s_add_u32 s30, s39, s12
	v_lshl_add_u64 v[6:7], s[6:7], 0, v[144:145]
	s_addc_u32 s31, s44, 0
	v_lshlrev_b64 v[6:7], 11, v[6:7]
	v_lshl_add_u64 v[6:7], s[30:31], 0, v[6:7]
	v_mov_b32_e32 v147, v177
	s_mov_b32 m0, s47
	v_mov_b32_e32 v1, s7
	v_or_b32_e32 v0, s6, v187
	v_lshl_add_u64 v[6:7], v[6:7], 0, v[146:147]
	s_waitcnt lgkmcnt(0)
	s_barrier
	global_load_lds_dwordx4 v[6:7], off
	v_lshl_add_u64 v[6:7], v[0:1], 0, s[10:11]
	v_lshl_add_u64 v[4:5], v[180:181], 0, s[12:13]
	v_lshlrev_b64 v[6:7], 11, v[6:7]
	v_lshl_add_u64 v[6:7], v[4:5], 0, v[6:7]
	s_mov_b32 m0, s50
	v_mov_b32_e32 v151, v177
	global_load_lds_dwordx4 v[6:7], off
	v_lshl_add_u64 v[6:7], s[6:7], 0, v[148:149]
	v_lshlrev_b64 v[6:7], 11, v[6:7]
	v_lshl_add_u64 v[6:7], s[30:31], 0, v[6:7]
	v_lshl_add_u64 v[6:7], v[6:7], 0, v[150:151]
	s_mov_b32 m0, s51
	v_mov_b32_e32 v155, v177
	global_load_lds_dwordx4 v[6:7], off
	v_lshl_add_u64 v[6:7], v[0:1], 0, s[16:17]
	v_lshlrev_b64 v[6:7], 11, v[6:7]
	v_lshl_add_u64 v[6:7], v[4:5], 0, v[6:7]
	s_mov_b32 m0, s52
	v_mov_b32_e32 v159, v177
	global_load_lds_dwordx4 v[6:7], off
	v_lshl_add_u64 v[6:7], s[6:7], 0, v[152:153]
	v_lshlrev_b64 v[6:7], 11, v[6:7]
	v_lshl_add_u64 v[6:7], s[30:31], 0, v[6:7]
	v_lshl_add_u64 v[6:7], v[6:7], 0, v[154:155]
	s_mov_b32 m0, s53
	v_mov_b32_e32 v163, v177
	global_load_lds_dwordx4 v[6:7], off
	v_lshl_add_u64 v[6:7], v[0:1], 0, s[18:19]
	v_lshlrev_b64 v[6:7], 11, v[6:7]
	v_lshl_add_u64 v[6:7], v[4:5], 0, v[6:7]
	s_mov_b32 m0, s54
	v_mov_b32_e32 v167, v177
	global_load_lds_dwordx4 v[6:7], off
	v_lshl_add_u64 v[6:7], s[6:7], 0, v[156:157]
	v_lshlrev_b64 v[6:7], 11, v[6:7]
	v_lshl_add_u64 v[6:7], s[30:31], 0, v[6:7]
	v_lshl_add_u64 v[6:7], v[6:7], 0, v[158:159]
	s_mov_b32 m0, s55
	v_mov_b32_e32 v171, v177
	global_load_lds_dwordx4 v[6:7], off
	v_lshl_add_u64 v[6:7], v[0:1], 0, s[20:21]
	v_lshlrev_b64 v[6:7], 11, v[6:7]
	v_lshl_add_u64 v[6:7], v[4:5], 0, v[6:7]
	s_mov_b32 m0, s56
	v_mov_b32_e32 v175, v177
	global_load_lds_dwordx4 v[6:7], off
	v_lshl_add_u64 v[6:7], s[6:7], 0, v[160:161]
	v_lshlrev_b64 v[6:7], 11, v[6:7]
	v_lshl_add_u64 v[6:7], s[30:31], 0, v[6:7]
	v_lshl_add_u64 v[6:7], v[6:7], 0, v[162:163]
	s_mov_b32 m0, s57
	s_nop 0
	global_load_lds_dwordx4 v[6:7], off
	v_lshl_add_u64 v[6:7], v[0:1], 0, s[22:23]
	v_lshlrev_b64 v[6:7], 11, v[6:7]
	v_lshl_add_u64 v[6:7], v[4:5], 0, v[6:7]
	s_mov_b32 m0, s58
	s_nop 0
	global_load_lds_dwordx4 v[6:7], off
	v_lshl_add_u64 v[6:7], s[6:7], 0, v[164:165]
	v_lshlrev_b64 v[6:7], 11, v[6:7]
	v_lshl_add_u64 v[6:7], s[30:31], 0, v[6:7]
	v_lshl_add_u64 v[6:7], v[6:7], 0, v[166:167]
	s_mov_b32 m0, s59
	s_nop 0
	global_load_lds_dwordx4 v[6:7], off
	v_lshl_add_u64 v[6:7], v[0:1], 0, s[24:25]
	v_lshlrev_b64 v[6:7], 11, v[6:7]
	v_lshl_add_u64 v[6:7], v[4:5], 0, v[6:7]
	s_mov_b32 m0, s60
	s_nop 0
	global_load_lds_dwordx4 v[6:7], off
	v_lshl_add_u64 v[6:7], s[6:7], 0, v[168:169]
	v_lshlrev_b64 v[6:7], 11, v[6:7]
	v_lshl_add_u64 v[6:7], s[30:31], 0, v[6:7]
	v_lshl_add_u64 v[6:7], v[6:7], 0, v[170:171]
	s_mov_b32 m0, s61
	s_nop 0
	global_load_lds_dwordx4 v[6:7], off
	v_lshl_add_u64 v[6:7], v[0:1], 0, s[26:27]
	v_lshlrev_b64 v[6:7], 11, v[6:7]
	v_lshl_add_u64 v[6:7], v[4:5], 0, v[6:7]
	s_mov_b32 m0, s62
	v_lshl_add_u64 v[0:1], v[0:1], 0, s[28:29]
	global_load_lds_dwordx4 v[6:7], off
	v_lshl_add_u64 v[6:7], s[6:7], 0, v[172:173]
	v_lshlrev_b64 v[6:7], 11, v[6:7]
	v_lshl_add_u64 v[6:7], s[30:31], 0, v[6:7]
	v_lshl_add_u64 v[6:7], v[6:7], 0, v[174:175]
	s_mov_b32 m0, s63
	v_lshlrev_b64 v[0:1], 11, v[0:1]
	global_load_lds_dwordx4 v[6:7], off
	v_lshl_add_u64 v[0:1], v[4:5], 0, v[0:1]
	s_mov_b32 m0, s64
	s_mov_b64 s[30:31], 0
	global_load_lds_dwordx4 v[0:1], off
	s_waitcnt vmcnt(0)
	s_mov_b64 s[6:7], -1
	s_waitcnt vmcnt(0) lgkmcnt(0)
	s_barrier

.LBB0_841:
	s_waitcnt lgkmcnt(3)
	v_mfma_f32_32x32x16_bf16 v[64:79], v[224:227], v[112:115], 0
	ds_read_b128 v[224:227], v171
	s_waitcnt lgkmcnt(3)
	v_mfma_f32_32x32x16_bf16 v[64:79], v[228:231], v[116:119], v[64:79]
	ds_read_b128 v[228:231], v175
	s_waitcnt lgkmcnt(3)
	v_mfma_f32_32x32x16_bf16 v[64:79], v[232:235], v[120:123], v[64:79]
	ds_read_b128 v[232:235], v176
	s_waitcnt lgkmcnt(3)
	v_mfma_f32_32x32x16_bf16 v[64:79], v[236:239], v[124:127], v[64:79]
	ds_read_b128 v[236:239], v185
	ds_read_b64_tr_b16 v[208:209], v241
	ds_read_b64_tr_b16 v[210:211], v241 offset:2048
	s_waitcnt lgkmcnt(5)
	v_mfma_f32_32x32x16_bf16 v[64:79], v[224:227], v[128:131], v[64:79]
	ds_read_b64_tr_b16 v[212:213], v241 offset:256
	ds_read_b64_tr_b16 v[214:215], v241 offset:2304
	s_waitcnt lgkmcnt(6)
	v_mfma_f32_32x32x16_bf16 v[64:79], v[228:231], v[132:135], v[64:79]
	ds_read_b64_tr_b16 v[216:217], v241 offset:512
	ds_read_b64_tr_b16 v[218:219], v241 offset:2560
	s_waitcnt lgkmcnt(7)
	v_mfma_f32_32x32x16_bf16 v[64:79], v[232:235], v[136:139], v[64:79]
	ds_read_b64_tr_b16 v[220:221], v241 offset:768
	ds_read_b64_tr_b16 v[222:223], v241 offset:2816
	s_waitcnt lgkmcnt(8)
	v_mfma_f32_32x32x16_bf16 v[64:79], v[236:239], v[140:143], v[64:79]
	v_add_u32_e32 v155, 0x2000, v155
	v_add_u32_e32 v159, 0x2000, v159
	v_add_u32_e32 v163, 0x2000, v163
	v_add_u32_e32 v167, 0x2000, v167
	v_add_u32_e32 v171, 0x2000, v171
	v_add_u32_e32 v175, 0x2000, v175
	v_add_u32_e32 v176, 0x2000, v176
	v_add_u32_e32 v185, 0x2000, v185
	s_nop 3
	v_exp_f32_e32 v224, v64
	v_exp_f32_e32 v225, v65
	v_exp_f32_e32 v226, v66
	v_exp_f32_e32 v227, v67
	v_exp_f32_e32 v228, v68
	v_exp_f32_e32 v229, v69
	v_exp_f32_e32 v230, v70
	v_exp_f32_e32 v231, v71
	v_exp_f32_e32 v232, v72
	v_exp_f32_e32 v233, v73
	v_exp_f32_e32 v234, v74
	v_exp_f32_e32 v235, v75
	v_exp_f32_e32 v236, v76
	v_exp_f32_e32 v237, v77
	v_exp_f32_e32 v238, v78
	v_exp_f32_e32 v239, v79
	v_cvt_pk_bf16_f32 v64, v224, v225
	v_cvt_pk_bf16_f32 v65, v226, v227
	v_cvt_pk_bf16_f32 v66, v228, v229
	v_cvt_pk_bf16_f32 v67, v230, v231
	v_cvt_pk_bf16_f32 v68, v232, v233
	v_cvt_pk_bf16_f32 v69, v234, v235
	v_cvt_pk_bf16_f32 v70, v236, v237
	v_cvt_pk_bf16_f32 v71, v238, v239
	s_waitcnt lgkmcnt(6)
	v_mfma_f32_32x32x16_bf16 v[48:63], v[208:211], v[64:67], v[48:63]
	ds_read_b64_tr_b16 v[208:209], v241 offset:4096
	ds_read_b64_tr_b16 v[210:211], v241 offset:6144
	v_add_f32_e32 v240, 0, v224
	v_add_f32_e32 v240, v225, v240
	v_add_f32_e32 v240, v226, v240
	v_add_f32_e32 v240, v227, v240
	v_add_f32_e32 v240, v228, v240
	s_waitcnt lgkmcnt(6)
	v_mfma_f32_32x32x16_bf16 v[32:47], v[212:215], v[64:67], v[32:47]
	ds_read_b64_tr_b16 v[212:213], v241 offset:4352
	ds_read_b64_tr_b16 v[214:215], v241 offset:6400
	v_add_f32_e32 v240, v229, v240
	v_add_f32_e32 v240, v230, v240
	v_add_f32_e32 v240, v231, v240
	v_add_f32_e32 v240, v232, v240
	s_waitcnt lgkmcnt(6)
	v_mfma_f32_32x32x16_bf16 v[16:31], v[216:219], v[64:67], v[16:31]
	ds_read_b64_tr_b16 v[216:217], v241 offset:4608
	ds_read_b64_tr_b16 v[218:219], v241 offset:6656
	v_add_f32_e32 v240, v233, v240
	v_add_f32_e32 v240, v234, v240
	v_add_f32_e32 v240, v235, v240
	v_add_f32_e32 v240, v236, v240
	s_waitcnt lgkmcnt(6)
	v_mfma_f32_32x32x16_bf16 v[0:15], v[220:223], v[64:67], v[0:15]
	ds_read_b64_tr_b16 v[220:221], v241 offset:4864
	ds_read_b64_tr_b16 v[222:223], v241 offset:6912
	v_add_f32_e32 v240, v237, v240
	v_add_f32_e32 v240, v238, v240
	v_add_f32_e32 v240, v239, v240
	v_add_f32_e32 v151, v151, v240
	s_waitcnt lgkmcnt(6)
	v_mfma_f32_32x32x16_bf16 v[48:63], v[208:211], v[68:71], v[48:63]
	ds_read_b128 v[224:227], v155
	s_waitcnt lgkmcnt(5)
	v_mfma_f32_32x32x16_bf16 v[32:47], v[212:215], v[68:71], v[32:47]
	ds_read_b128 v[228:231], v159
	s_waitcnt lgkmcnt(4)
	v_mfma_f32_32x32x16_bf16 v[16:31], v[216:219], v[68:71], v[16:31]
	ds_read_b128 v[232:235], v163
	s_waitcnt lgkmcnt(3)
	v_mfma_f32_32x32x16_bf16 v[0:15], v[220:223], v[68:71], v[0:15]
	ds_read_b128 v[236:239], v167
	v_add_u32_e32 v241, 0x2000, v241
	s_addk_i32 s8, 0x2000
	s_cmp_lg_u32 s8, 0x10000
	s_cbranch_scc1 .LBB0_841
	s_waitcnt lgkmcnt(0)
	ds_bpermute_b32 v66, v191, v151
	v_lshrrev_b32_e32 v65, 2, v207
	v_cmp_ne_u32_e32 vcc, -1, v207
	v_and_b32_e32 v64, 3, v207
	v_lshl_add_u32 v65, s68, 13, v65
	v_mad_u64_u32 v[64:65], s[8:9], v65, 3, v[64:65]
	s_and_b64 s[30:31], vcc, s[4:5]
	s_and_saveexec_b64 s[8:9], s[30:31]
	s_cbranch_execz .LBB0_844
	v_ashrrev_i32_e32 v65, 31, v64
	s_waitcnt lgkmcnt(0)
	v_add_f32_e32 v68, v151, v66
	v_lshl_add_u64 v[66:67], v[64:65], 2, s[36:37]
	global_store_dword v[66:67], v68, off
	s_add_u32 s98, s98, 1
.LBB0_844:
	s_or_b64 exec, exec, s[8:9]
	v_cvt_pk_bf16_f32 v48, v48, v49
	v_cvt_pk_bf16_f32 v49, v50, v51
	ds_write_b64 v204, v[48:49]
	v_cvt_pk_bf16_f32 v48, v52, v53
	v_cvt_pk_bf16_f32 v49, v54, v55
	v_cndmask_b32_e32 v64, -1, v64, vcc
	ds_write_b64 v204, v[48:49] offset:16
	v_cvt_pk_bf16_f32 v48, v56, v57
	v_cvt_pk_bf16_f32 v49, v58, v59
	ds_bpermute_b32 v176, v188, v64
	ds_write_b64 v204, v[48:49] offset:32
	v_cvt_pk_bf16_f32 v48, v60, v61
	v_cvt_pk_bf16_f32 v49, v62, v63
	ds_write_b64 v204, v[48:49] offset:48
	s_waitcnt lgkmcnt(0)
	ds_bpermute_b32 v64, v189, v64
	ds_read_b128 v[48:51], v205
	s_waitcnt lgkmcnt(4)
	v_lshlrev_b64 v[52:53], 8, v[176:177]
	v_cmp_lt_i32_e32 vcc, -1, v176
	v_lshl_add_u64 v[52:53], v[182:183], 0, v[52:53]
	v_add_u32_e32 v56, v179, v178
	s_and_saveexec_b64 s[8:9], vcc
	s_cbranch_execz .LBB0_846
	ds_read_b128 v[58:61], v56
	s_waitcnt lgkmcnt(0)
	global_store_dwordx4 v[52:53], v[58:61], off
	s_add_u32 s98, s98, 1
.LBB0_846:
	s_or_b64 exec, exec, s[8:9]
	v_mov_b32_e32 v65, v177
	s_waitcnt lgkmcnt(1)
	v_lshlrev_b64 v[54:55], 8, v[64:65]
	v_cmp_lt_i32_e64 s[8:9], -1, v64
	v_lshl_add_u64 v[54:55], v[182:183], 0, v[54:55]
	s_and_saveexec_b64 s[30:31], s[8:9]
	s_cbranch_execz .LBB0_848
	s_waitcnt lgkmcnt(0)
	global_store_dwordx4 v[54:55], v[48:51], off
	s_add_u32 s98, s98, 1
.LBB0_848:
	s_or_b64 exec, exec, s[30:31]
	s_waitcnt lgkmcnt(0)
	v_cvt_pk_bf16_f32 v32, v32, v33
	v_cvt_pk_bf16_f32 v33, v34, v35
	ds_write_b64 v204, v[32:33]
	v_cvt_pk_bf16_f32 v32, v36, v37
	v_cvt_pk_bf16_f32 v33, v38, v39
	ds_write_b64 v204, v[32:33] offset:16
	v_cvt_pk_bf16_f32 v32, v40, v41
	v_cvt_pk_bf16_f32 v33, v42, v43
	ds_write_b64 v204, v[32:33] offset:32
	v_cvt_pk_bf16_f32 v32, v44, v45
	v_cvt_pk_bf16_f32 v33, v46, v47
	ds_write_b64 v204, v[32:33] offset:48
	s_waitcnt lgkmcnt(0)
	ds_read_b128 v[32:35], v205
	s_and_saveexec_b64 s[30:31], vcc
	s_cbranch_execz .LBB0_850
	ds_read_b128 v[36:39], v56
	s_waitcnt lgkmcnt(0)
	global_store_dwordx4 v[52:53], v[36:39], off offset:64
	s_add_u32 s98, s98, 1
.LBB0_850:
	s_or_b64 exec, exec, s[30:31]
	s_and_saveexec_b64 s[30:31], s[8:9]
	s_cbranch_execz .LBB0_852
	s_waitcnt lgkmcnt(0)
	global_store_dwordx4 v[54:55], v[32:35], off offset:64
	s_add_u32 s98, s98, 1
.LBB0_852:
	s_or_b64 exec, exec, s[30:31]
	s_waitcnt lgkmcnt(0)
	v_cvt_pk_bf16_f32 v16, v16, v17
	v_cvt_pk_bf16_f32 v17, v18, v19
	ds_write_b64 v204, v[16:17]
	v_cvt_pk_bf16_f32 v16, v20, v21
	v_cvt_pk_bf16_f32 v17, v22, v23
	ds_write_b64 v204, v[16:17] offset:16
	v_cvt_pk_bf16_f32 v16, v24, v25
	v_cvt_pk_bf16_f32 v17, v26, v27
	ds_write_b64 v204, v[16:17] offset:32
	v_cvt_pk_bf16_f32 v16, v28, v29
	v_cvt_pk_bf16_f32 v17, v30, v31
	ds_write_b64 v204, v[16:17] offset:48
	s_waitcnt lgkmcnt(0)
	ds_read_b128 v[16:19], v205
	s_and_saveexec_b64 s[30:31], vcc
	s_cbranch_execz .LBB0_854
	ds_read_b128 v[20:23], v56
	s_waitcnt lgkmcnt(0)
	global_store_dwordx4 v[52:53], v[20:23], off offset:128
	s_add_u32 s98, s98, 1
.LBB0_854:
	s_or_b64 exec, exec, s[30:31]
	s_and_saveexec_b64 s[30:31], s[8:9]
	s_cbranch_execz .LBB0_856
	s_waitcnt lgkmcnt(0)
	global_store_dwordx4 v[54:55], v[16:19], off offset:128
	s_add_u32 s98, s98, 1
.LBB0_856:
	s_or_b64 exec, exec, s[30:31]
	s_waitcnt lgkmcnt(0)
	v_cvt_pk_bf16_f32 v0, v0, v1
	v_cvt_pk_bf16_f32 v1, v2, v3
	ds_write_b64 v204, v[0:1]
	v_cvt_pk_bf16_f32 v0, v4, v5
	v_cvt_pk_bf16_f32 v1, v6, v7
	ds_write_b64 v204, v[0:1] offset:16
	v_cvt_pk_bf16_f32 v0, v8, v9
	v_cvt_pk_bf16_f32 v1, v10, v11
	ds_write_b64 v204, v[0:1] offset:32
	v_cvt_pk_bf16_f32 v0, v12, v13
	v_cvt_pk_bf16_f32 v1, v14, v15
	ds_write_b64 v204, v[0:1] offset:48
	s_waitcnt lgkmcnt(0)
	ds_read_b128 v[0:3], v205
	s_and_saveexec_b64 s[30:31], vcc
	s_cbranch_execz .LBB0_858
	ds_read_b128 v[4:7], v56
	s_waitcnt lgkmcnt(0)
	global_store_dwordx4 v[52:53], v[4:7], off offset:192
	s_add_u32 s98, s98, 1
.LBB0_858:
	s_or_b64 exec, exec, s[30:31]
	s_and_saveexec_b64 s[30:31], s[8:9]
	s_cbranch_execz .LBB0_822
	s_waitcnt lgkmcnt(0)
	global_store_dwordx4 v[54:55], v[0:3], off offset:192
	s_add_u32 s98, s98, 1
	s_branch .LBB0_822
